# attention block: Q fragments of the next 16-query step are prefetched one step ahead (counted wait instead of vmcnt(0) at the top of each step)
# baseline (speedup 1.0000x reference)
.LBB0_984:
	s_or_b64 exec, exec, s[12:13]
	s_waitcnt vmcnt(0)
	ds_write_b16 v83, v0
	ds_write_b16_d16_hi v83, v0 offset:592
	ds_write_b16 v83, v1 offset:1184
	ds_write_b16_d16_hi v83, v1 offset:1776
	ds_write_b16 v83, v2 offset:2368
	ds_write_b16_d16_hi v83, v2 offset:2960
	ds_write_b16 v83, v3 offset:3552
	ds_write_b16_d16_hi v83, v3 offset:4144
	ds_write_b64 v74, v[88:89] offset:512
	v_lshl_add_u32 v0, s35, 2, v96
	v_readlane_b32 s52, v235, 1
	v_lshlrev_b32_e32 v1, 2, v0
	v_readlane_b32 s60, v235, 9
	v_readlane_b32 s61, v235, 10
	s_waitcnt lgkmcnt(0)
	s_barrier
	s_lshr_b32 s6, s29, 2
	s_and_b32 s8, s14, 0xfffff000
	s_nop 0
	global_load_dword v53, v1, s[60:61]
	v_add_u32_e32 v1, 1, v0
	v_cvt_f32_u32_e32 v1, v1
	s_lshl_b32 s7, s35, 6
	v_or_b32_e32 v2, s8, v81
	s_and_b32 s6, s6, 31
	v_mul_f32_e32 v3, -0.5, v1
	v_cmp_gt_f32_e32 vcc, s17, v3
	v_lshl_or_b32 v55, s6, 7, v2
	v_lshlrev_b32_e32 v44, 7, v0
	v_cndmask_b32_e32 v3, 0, v84, vcc
	v_fmac_f32_e32 v3, -0.5, v1
	v_exp_f32_e32 v1, v3
	v_cndmask_b32_e32 v2, 0, v85, vcc
	s_lshl_b32 s8, s7, 1
	v_lshl_add_u64 v[66:67], v[46:47], 0, v[44:45]
	v_ldexp_f32 v63, v1, v2
	v_lshl_add_u64 v[68:69], v[48:49], 0, v[44:45]
	v_lshl_add_u64 v[70:71], v[46:47], 0, s[8:9]
	v_mov_b32_e32 v44, v80
	v_mov_b32_e32 v57, v78
	v_readlane_b32 s53, v235, 2
	v_readlane_b32 s54, v235, 3
	v_readlane_b32 s55, v235, 4
	v_readlane_b32 s56, v235, 5
	v_readlane_b32 s57, v235, 6
	v_readlane_b32 s58, v235, 7
	v_readlane_b32 s59, v235, 8
	v_readlane_b32 s62, v235, 11
	v_readlane_b32 s63, v235, 12
	v_readlane_b32 s64, v235, 13
	v_readlane_b32 s65, v235, 14
	v_readlane_b32 s66, v235, 15
	v_readlane_b32 s67, v235, 16
	v_mad_i64_i32 v[244:245], s[6:7], v55, s16, v[66:67]
	global_load_dwordx4 v[236:239], v[244:245], off
	global_load_dwordx4 v[240:243], v[244:245], off offset:64
.LBB0_985:
	s_lshl_b32 s79, s33, 7
	v_add_u32_e32 v134, s79, v132
	v_add_u32_e32 v135, s79, v133
	v_add_u32_e32 v72, s33, v55
	v_mad_i64_i32 v[0:1], s[6:7], v72, s16, v[66:67]
	s_cmp_lg_u32 s33, 0
	s_cbranch_scc1 .LAQ_w
	s_waitcnt vmcnt(0)
.LAQ_w:
	s_waitcnt vmcnt(4)
	v_mov_b32_e32 v32, v236
	v_mov_b32_e32 v33, v237
	v_mov_b32_e32 v34, v238
	v_mov_b32_e32 v35, v239
	v_mov_b32_e32 v40, v240
	v_mov_b32_e32 v41, v241
	v_mov_b32_e32 v42, v242
	v_mov_b32_e32 v43, v243
	v_mov_b32_e32 v246, 0x5c000
	v_add_co_u32_e64 v244, s[6:7], v246, v0
	s_nop 1
	v_addc_co_u32_e64 v245, s[6:7], 0, v1, s[6:7]
	global_load_dwordx4 v[236:239], v[244:245], off
	global_load_dwordx4 v[240:243], v[244:245], off offset:64
	v_add_u32_e32 v0, 0xffffff80, v72
	v_max_i32_e32 v0, 0, v0
	v_mad_u64_u32 v[4:5], s[6:7], v0, s16, v[70:71]
	ds_read_b128 v[0:3], v134 offset:0
	s_nop 0
	ds_read_b128 v[4:7], v135 offset:0
	v_add_u32_e32 v59, s33, v75
	v_add_u32_e32 v61, 16, v72
	v_cmp_lt_u32_e32 vcc, s18, v59
	v_mov_b32_e32 v62, s31
	v_ashrrev_i32_e32 v73, 31, v72
	v_cndmask_b32_e32 v61, v61, v62, vcc
	v_max_i32_e32 v61, 0, v61
	v_mad_u64_u32 v[94:95], s[6:7], v61, s16, v[70:71]
	s_waitcnt lgkmcnt(1)
	v_mfma_f32_16x16x32_bf16 v[0:3], v[0:3], v[32:35], 0
	s_waitcnt lgkmcnt(0)
	v_mfma_f32_16x16x32_bf16 v[36:39], v[4:7], v[40:43], v[0:3]
	s_nop 5
	v_add_u32_e32 v0, 0xffffff90, v72
	v_max_i32_e32 v0, 0, v0
	v_mad_u64_u32 v[4:5], s[6:7], v0, s16, v[70:71]
	ds_read_b128 v[0:3], v134 offset:2048
	s_nop 0
	ds_read_b128 v[4:7], v135 offset:2048
	v_mov_b32_e32 v62, v36
	s_waitcnt lgkmcnt(1)
	v_mfma_f32_16x16x32_bf16 v[0:3], v[0:3], v[32:35], 0
	s_waitcnt lgkmcnt(0)
	v_mfma_f32_16x16x32_bf16 v[28:31], v[4:7], v[40:43], v[0:3]
	s_nop 5
	v_add_u32_e32 v0, 0xffffffa0, v72
	v_max_i32_e32 v0, 0, v0
	v_mad_u64_u32 v[4:5], s[6:7], v0, s16, v[70:71]
	ds_read_b128 v[0:3], v134 offset:4096
	s_nop 0
	ds_read_b128 v[4:7], v135 offset:4096
	s_waitcnt lgkmcnt(1)
	v_mfma_f32_16x16x32_bf16 v[0:3], v[0:3], v[32:35], 0
	s_waitcnt lgkmcnt(0)
	v_mfma_f32_16x16x32_bf16 v[24:27], v[4:7], v[40:43], v[0:3]
	s_nop 5
	v_add_u32_e32 v0, 0xffffffb0, v72
	v_max_i32_e32 v0, 0, v0
	v_mad_u64_u32 v[4:5], s[6:7], v0, s16, v[70:71]
	ds_read_b128 v[0:3], v134 offset:6144
	s_nop 0
	ds_read_b128 v[4:7], v135 offset:6144
	s_waitcnt lgkmcnt(1)
	v_mfma_f32_16x16x32_bf16 v[0:3], v[0:3], v[32:35], 0
	s_waitcnt lgkmcnt(0)
	v_mfma_f32_16x16x32_bf16 v[20:23], v[4:7], v[40:43], v[0:3]
	s_nop 5
	v_subrev_u32_e32 v0, 64, v72
	v_max_i32_e32 v0, 0, v0
	v_mad_u64_u32 v[4:5], s[6:7], v0, s16, v[70:71]
	ds_read_b128 v[0:3], v134 offset:8192
	s_nop 0
	ds_read_b128 v[4:7], v135 offset:8192
	s_waitcnt lgkmcnt(1)
	v_mfma_f32_16x16x32_bf16 v[0:3], v[0:3], v[32:35], 0
	s_waitcnt lgkmcnt(0)
	v_mfma_f32_16x16x32_bf16 v[16:19], v[4:7], v[40:43], v[0:3]
	s_nop 5
	v_subrev_u32_e32 v0, 48, v72
	v_max_i32_e32 v0, 0, v0
	v_mad_u64_u32 v[4:5], s[6:7], v0, s16, v[70:71]
	ds_read_b128 v[0:3], v134 offset:10240
	s_nop 0
	ds_read_b128 v[4:7], v135 offset:10240
	s_waitcnt lgkmcnt(1)
	v_mfma_f32_16x16x32_bf16 v[0:3], v[0:3], v[32:35], 0
	s_waitcnt lgkmcnt(0)
	v_mfma_f32_16x16x32_bf16 v[12:15], v[4:7], v[40:43], v[0:3]
	s_nop 5
	v_subrev_u32_e32 v0, 32, v72
	v_max_i32_e32 v0, 0, v0
	v_mad_u64_u32 v[4:5], s[6:7], v0, s16, v[70:71]
	ds_read_b128 v[0:3], v134 offset:12288
	s_nop 0
	ds_read_b128 v[4:7], v135 offset:12288
	s_waitcnt lgkmcnt(1)
	v_mfma_f32_16x16x32_bf16 v[0:3], v[0:3], v[32:35], 0
	s_waitcnt lgkmcnt(0)
	v_mfma_f32_16x16x32_bf16 v[8:11], v[4:7], v[40:43], v[0:3]
	s_nop 5
	v_add_u32_e32 v0, -16, v72
	v_max_i32_e32 v0, 0, v0
	v_mad_u64_u32 v[4:5], s[6:7], v0, s16, v[70:71]
	ds_read_b128 v[0:3], v134 offset:14336
	s_nop 0
	ds_read_b128 v[4:7], v135 offset:14336
	s_waitcnt lgkmcnt(1)
	v_mfma_f32_16x16x32_bf16 v[0:3], v[0:3], v[32:35], 0
	s_waitcnt lgkmcnt(0)
	v_mfma_f32_16x16x32_bf16 v[4:7], v[4:7], v[40:43], v[0:3]
	s_nop 5
	v_max_i32_e32 v0, 0, v72
	v_mad_u64_u32 v[90:91], s[6:7], v0, s16, v[70:71]
	ds_read_b128 v[0:3], v134 offset:16384
	s_nop 0
	ds_read_b128 v[90:93], v135 offset:16384
	v_cmp_lt_u32_e64 s[6:7], s26, v59
	s_or_b64 s[6:7], s[10:11], s[6:7]
	s_waitcnt lgkmcnt(1)
	v_mfma_f32_16x16x32_bf16 v[0:3], v[0:3], v[32:35], 0
	s_waitcnt lgkmcnt(0)
	v_mfma_f32_16x16x32_bf16 v[0:3], v[90:93], v[40:43], v[0:3]
	ds_read_b128 v[90:93], v134 offset:18432
	ds_read_b128 v[98:101], v135 offset:18432
	ds_read2_b64 v[106:109], v57 offset0:8 offset1:12
	s_waitcnt lgkmcnt(2)
	v_mfma_f32_16x16x32_bf16 v[32:35], v[90:93], v[32:35], 0
	s_waitcnt lgkmcnt(1)
	v_mfma_f32_16x16x32_bf16 v[32:35], v[98:101], v[40:43], v[32:35]
	v_add_u32_e32 v40, s33, v81
	v_add_u32_e32 v42, 0x80, v40
	v_add_u32_e32 v40, s33, v79
	v_sub_u32_e32 v43, v42, v40
	v_cvt_f32_i32_e32 v61, v43
	v_cmp_gt_u32_e32 vcc, s19, v43
	s_and_b64 vcc, s[10:11], vcc
	s_add_i32 s33, s33, 16
	v_pk_mul_f32 v[40:41], v[62:63], v[60:61]
	v_mov_b32_e32 v62, v37
	v_sub_f32_e32 v36, v40, v41
	v_add_u32_e32 v41, v42, v44
	v_cndmask_b32_e32 v40, v86, v36, vcc
	v_add_u32_e32 v36, 0x90, v41
	v_cvt_f32_i32_e32 v61, v36
	v_cmp_gt_u32_e32 vcc, s19, v36
	s_and_b64 vcc, s[10:11], vcc
	v_add_u32_e32 v44, -16, v44
	v_pk_mul_f32 v[36:37], v[62:63], v[60:61]
	v_mov_b32_e32 v62, v38
	v_sub_f32_e32 v36, v36, v37
	v_cndmask_b32_e32 v42, v86, v36, vcc
	v_add_u32_e32 v36, -2, v43
	v_cvt_f32_i32_e32 v61, v36
	v_cmp_gt_u32_e32 vcc, s19, v36
	s_and_b64 vcc, s[10:11], vcc
	v_max3_f32 v87, v53, v40, v42
	v_pk_mul_f32 v[36:37], v[62:63], v[60:61]
	v_mov_b32_e32 v62, v39
	v_sub_f32_e32 v36, v36, v37
	v_cndmask_b32_e32 v38, v86, v36, vcc
	v_add_u32_e32 v36, -3, v43
	v_cvt_f32_i32_e32 v61, v36
	v_cmp_gt_u32_e32 vcc, s19, v36
	s_and_b64 vcc, s[10:11], vcc
	v_pk_mul_f32 v[36:37], v[62:63], v[60:61]
	s_nop 0
	v_sub_f32_e32 v36, v36, v37
	v_cndmask_b32_e32 v39, v86, v36, vcc
	v_add_u32_e32 v36, -16, v43
	v_cvt_f32_i32_e32 v61, v36
	v_mov_b32_e32 v62, v28
	v_cmp_gt_u32_e32 vcc, s19, v36
	s_and_b64 vcc, vcc, s[6:7]
	v_pk_mul_f32 v[36:37], v[62:63], v[60:61]
	v_mov_b32_e32 v62, v29
	v_sub_f32_e32 v28, v36, v37
	v_cndmask_b32_e32 v36, v86, v28, vcc
	v_add_u32_e32 v28, 0x80, v41
	v_cvt_f32_i32_e32 v61, v28
	v_cmp_gt_u32_e32 vcc, s19, v28
	s_and_b64 vcc, vcc, s[6:7]
	v_max3_f32 v87, v87, v38, v39
	v_pk_mul_f32 v[28:29], v[62:63], v[60:61]
	v_mov_b32_e32 v62, v30
	v_sub_f32_e32 v28, v28, v29
	v_cndmask_b32_e32 v37, v86, v28, vcc
	v_subrev_u32_e32 v28, 18, v43
	v_cvt_f32_i32_e32 v61, v28
	v_cmp_gt_u32_e32 vcc, s19, v28
	s_and_b64 vcc, vcc, s[6:7]
	v_max3_f32 v87, v87, v36, v37
	v_pk_mul_f32 v[28:29], v[62:63], v[60:61]
	v_mov_b32_e32 v62, v31
	v_sub_f32_e32 v28, v28, v29
	v_cndmask_b32_e32 v30, v86, v28, vcc
	v_subrev_u32_e32 v28, 19, v43
	v_cvt_f32_i32_e32 v61, v28
	v_cmp_gt_u32_e32 vcc, s19, v28
	s_and_b64 vcc, vcc, s[6:7]
	v_cmp_lt_u32_e64 s[6:7], s27, v59
	v_pk_mul_f32 v[28:29], v[62:63], v[60:61]
	v_mov_b32_e32 v62, v24
	v_sub_f32_e32 v28, v28, v29
	v_cndmask_b32_e32 v31, v86, v28, vcc
	v_subrev_u32_e32 v28, 32, v43
	v_cvt_f32_i32_e32 v61, v28
	v_cmp_gt_u32_e32 vcc, s19, v28
	s_or_b64 s[6:7], s[10:11], s[6:7]
	s_and_b64 vcc, vcc, s[6:7]
	v_pk_mul_f32 v[28:29], v[62:63], v[60:61]
	v_mov_b32_e32 v62, v25
	v_sub_f32_e32 v24, v28, v29
	v_cndmask_b32_e32 v28, v86, v24, vcc
	v_add_u32_e32 v24, 0x70, v41
	v_cvt_f32_i32_e32 v61, v24
	v_cmp_gt_u32_e32 vcc, s19, v24
	s_and_b64 vcc, vcc, s[6:7]
	v_max3_f32 v87, v87, v30, v31
	v_pk_mul_f32 v[24:25], v[62:63], v[60:61]
	v_mov_b32_e32 v62, v26
	v_sub_f32_e32 v24, v24, v25
	v_cndmask_b32_e32 v29, v86, v24, vcc
	v_subrev_u32_e32 v24, 34, v43
	v_cvt_f32_i32_e32 v61, v24
	v_cmp_gt_u32_e32 vcc, s19, v24
	s_and_b64 vcc, vcc, s[6:7]
	v_max3_f32 v87, v87, v28, v29
	v_pk_mul_f32 v[24:25], v[62:63], v[60:61]
	v_mov_b32_e32 v62, v27
	v_sub_f32_e32 v24, v24, v25
	v_cndmask_b32_e32 v26, v86, v24, vcc
	v_subrev_u32_e32 v24, 35, v43
	v_cvt_f32_i32_e32 v61, v24
	v_cmp_gt_u32_e32 vcc, s19, v24
	s_and_b64 vcc, vcc, s[6:7]
	v_cmp_lt_u32_e64 s[6:7], s28, v59
	v_pk_mul_f32 v[24:25], v[62:63], v[60:61]
	v_mov_b32_e32 v62, v20
	v_sub_f32_e32 v24, v24, v25
	v_cndmask_b32_e32 v90, v86, v24, vcc
	v_subrev_u32_e32 v24, 48, v43
	v_cvt_f32_i32_e32 v61, v24
	v_cmp_gt_u32_e32 vcc, s19, v24
	s_or_b64 s[6:7], s[10:11], s[6:7]
	s_and_b64 vcc, vcc, s[6:7]
	v_pk_mul_f32 v[24:25], v[62:63], v[60:61]
	v_mov_b32_e32 v62, v21
	v_sub_f32_e32 v20, v24, v25
	v_cndmask_b32_e32 v24, v86, v20, vcc
	v_add_u32_e32 v20, 0x60, v41
	v_cvt_f32_i32_e32 v61, v20
	v_cmp_gt_u32_e32 vcc, s19, v20
	s_and_b64 vcc, vcc, s[6:7]
	v_max3_f32 v27, v87, v26, v90
	v_pk_mul_f32 v[20:21], v[62:63], v[60:61]
	v_mov_b32_e32 v62, v22
	v_sub_f32_e32 v20, v20, v21
	v_cndmask_b32_e32 v87, v86, v20, vcc
	v_subrev_u32_e32 v20, 50, v43
	v_cvt_f32_i32_e32 v61, v20
	v_cmp_gt_u32_e32 vcc, s19, v20
	s_and_b64 vcc, vcc, s[6:7]
	v_max3_f32 v25, v27, v24, v87
	v_pk_mul_f32 v[20:21], v[62:63], v[60:61]
	v_mov_b32_e32 v62, v23
	v_sub_f32_e32 v20, v20, v21
	v_cndmask_b32_e32 v22, v86, v20, vcc
	v_subrev_u32_e32 v20, 51, v43
	v_cvt_f32_i32_e32 v61, v20
	v_cmp_gt_u32_e32 vcc, s19, v20
	s_and_b64 vcc, vcc, s[6:7]
	v_cmp_lt_u32_e64 s[6:7], 48, v59
	v_pk_mul_f32 v[20:21], v[62:63], v[60:61]
	v_mov_b32_e32 v62, v16
	v_sub_f32_e32 v20, v20, v21
	v_cndmask_b32_e32 v23, v86, v20, vcc
	v_subrev_u32_e32 v20, 64, v43
	v_cvt_f32_i32_e32 v61, v20
	v_cmp_gt_u32_e32 vcc, s19, v20
	s_or_b64 s[6:7], s[10:11], s[6:7]
	s_and_b64 vcc, vcc, s[6:7]
	v_pk_mul_f32 v[20:21], v[62:63], v[60:61]
	v_mov_b32_e32 v62, v17
	v_sub_f32_e32 v16, v20, v21
	v_cndmask_b32_e32 v20, v86, v16, vcc
	v_add_u32_e32 v16, 0x50, v41
	v_cvt_f32_i32_e32 v61, v16
	v_cmp_gt_u32_e32 vcc, s19, v16
	s_and_b64 vcc, vcc, s[6:7]
	v_max3_f32 v25, v25, v22, v23
	v_pk_mul_f32 v[16:17], v[62:63], v[60:61]
	v_mov_b32_e32 v62, v18
	v_sub_f32_e32 v16, v16, v17
	v_cndmask_b32_e32 v21, v86, v16, vcc
	v_add_u32_e32 v16, 0xffffffbe, v43
	v_cvt_f32_i32_e32 v61, v16
	v_cmp_gt_u32_e32 vcc, s19, v16
	s_and_b64 vcc, vcc, s[6:7]
	v_max3_f32 v25, v25, v20, v21
	v_pk_mul_f32 v[16:17], v[62:63], v[60:61]
	v_mov_b32_e32 v62, v19
	v_sub_f32_e32 v16, v16, v17
	v_cndmask_b32_e32 v18, v86, v16, vcc
	v_add_u32_e32 v16, 0xffffffbd, v43
	v_cvt_f32_i32_e32 v61, v16
	v_cmp_gt_u32_e32 vcc, s19, v16
	s_and_b64 vcc, vcc, s[6:7]
	v_cmp_lt_u32_e64 s[6:7], 47, v59
	v_pk_mul_f32 v[16:17], v[62:63], v[60:61]
	v_mov_b32_e32 v62, v12
	v_sub_f32_e32 v16, v16, v17
	v_cndmask_b32_e32 v19, v86, v16, vcc
	v_add_u32_e32 v16, 0xffffffb0, v43
	v_cvt_f32_i32_e32 v61, v16
	v_cmp_gt_u32_e32 vcc, s19, v16
	s_or_b64 s[6:7], s[10:11], s[6:7]
	s_and_b64 vcc, vcc, s[6:7]
	v_pk_mul_f32 v[16:17], v[62:63], v[60:61]
	v_mov_b32_e32 v62, v13
	v_sub_f32_e32 v12, v16, v17
	v_cndmask_b32_e32 v16, v86, v12, vcc
	v_add_u32_e32 v12, 64, v41
	v_cvt_f32_i32_e32 v61, v12
	v_cmp_gt_u32_e32 vcc, s19, v12
	s_and_b64 vcc, vcc, s[6:7]
	v_max3_f32 v25, v25, v18, v19
	v_pk_mul_f32 v[12:13], v[62:63], v[60:61]
	v_mov_b32_e32 v62, v14
	v_sub_f32_e32 v12, v12, v13
	v_cndmask_b32_e32 v17, v86, v12, vcc
	v_add_u32_e32 v12, 0xffffffae, v43
	v_cvt_f32_i32_e32 v61, v12
	v_cmp_gt_u32_e32 vcc, s19, v12
	s_and_b64 vcc, vcc, s[6:7]
	v_max3_f32 v25, v25, v16, v17
	v_pk_mul_f32 v[12:13], v[62:63], v[60:61]
	v_mov_b32_e32 v62, v15
	v_sub_f32_e32 v12, v12, v13
	v_cndmask_b32_e32 v14, v86, v12, vcc
	v_add_u32_e32 v12, 0xffffffad, v43
	v_cvt_f32_i32_e32 v61, v12
	v_cmp_gt_u32_e32 vcc, s19, v12
	s_and_b64 vcc, vcc, s[6:7]
	v_cmp_lt_u32_e64 s[6:7], 16, v59
	v_pk_mul_f32 v[12:13], v[62:63], v[60:61]
	v_mov_b32_e32 v62, v8
	v_sub_f32_e32 v12, v12, v13
	v_cndmask_b32_e32 v15, v86, v12, vcc
	v_add_u32_e32 v12, 0xffffffa0, v43
	v_cvt_f32_i32_e32 v61, v12
	v_cmp_gt_u32_e32 vcc, s19, v12
	s_or_b64 s[6:7], s[10:11], s[6:7]
	s_and_b64 vcc, vcc, s[6:7]
	v_pk_mul_f32 v[12:13], v[62:63], v[60:61]
	v_mov_b32_e32 v62, v9
	v_sub_f32_e32 v8, v12, v13
	v_cndmask_b32_e32 v12, v86, v8, vcc
	v_add_u32_e32 v8, 48, v41
	v_cvt_f32_i32_e32 v61, v8
	v_cmp_gt_u32_e32 vcc, s19, v8
	s_and_b64 vcc, vcc, s[6:7]
	v_max3_f32 v25, v25, v14, v15
	v_pk_mul_f32 v[8:9], v[62:63], v[60:61]
	v_mov_b32_e32 v62, v10
	v_sub_f32_e32 v8, v8, v9
	v_cndmask_b32_e32 v13, v86, v8, vcc
	v_add_u32_e32 v8, 0xffffff9e, v43
	v_cvt_f32_i32_e32 v61, v8
	v_cmp_gt_u32_e32 vcc, s19, v8
	s_and_b64 vcc, vcc, s[6:7]
	v_max3_f32 v25, v25, v12, v13
	v_pk_mul_f32 v[8:9], v[62:63], v[60:61]
	v_mov_b32_e32 v62, v11
	v_sub_f32_e32 v8, v8, v9
	v_cndmask_b32_e32 v10, v86, v8, vcc
	v_add_u32_e32 v8, 0xffffff9d, v43
	v_cvt_f32_i32_e32 v61, v8
	v_cmp_gt_u32_e32 vcc, s19, v8
	s_and_b64 vcc, vcc, s[6:7]
	v_pk_mul_f32 v[8:9], v[62:63], v[60:61]
	s_nop 0
	v_sub_f32_e32 v8, v8, v9
	v_cndmask_b32_e32 v11, v86, v8, vcc
	v_add_u32_e32 v8, 0xffffff90, v43
	v_cvt_f32_i32_e32 v61, v8
	v_or_b32_e32 v9, s30, v59
	v_mov_b32_e32 v62, v4
	v_cmp_gt_u32_e32 vcc, s19, v8
	v_cmp_ne_u32_e64 s[6:7], 0, v9
	v_pk_mul_f32 v[8:9], v[62:63], v[60:61]
	s_and_b64 vcc, s[6:7], vcc
	v_sub_f32_e32 v4, v8, v9
	v_cndmask_b32_e32 v8, v86, v4, vcc
	v_add_u32_e32 v4, 32, v41
	v_cvt_f32_i32_e32 v61, v4
	v_mov_b32_e32 v62, v5
	v_cmp_gt_u32_e32 vcc, s19, v4
	s_and_b64 vcc, s[6:7], vcc
	v_pk_mul_f32 v[4:5], v[62:63], v[60:61]
	v_mov_b32_e32 v62, v6
	v_sub_f32_e32 v4, v4, v5
	v_cndmask_b32_e32 v9, v86, v4, vcc
	v_add_u32_e32 v4, 0xffffff8e, v43
	v_cvt_f32_i32_e32 v61, v4
	v_cmp_gt_u32_e32 vcc, s19, v4
	s_and_b64 vcc, s[6:7], vcc
	v_max3_f32 v25, v25, v10, v11
	v_pk_mul_f32 v[4:5], v[62:63], v[60:61]
	v_mov_b32_e32 v62, v7
	v_sub_f32_e32 v4, v4, v5
	v_cndmask_b32_e32 v6, v86, v4, vcc
	v_add_u32_e32 v4, 0xffffff8d, v43
	v_cvt_f32_i32_e32 v61, v4
	v_cmp_gt_u32_e32 vcc, s19, v4
	s_and_b64 vcc, s[6:7], vcc
	v_max3_f32 v25, v25, v8, v9
	v_pk_mul_f32 v[4:5], v[62:63], v[60:61]
	v_mov_b32_e32 v62, v0
	v_sub_f32_e32 v4, v4, v5
	v_cndmask_b32_e32 v7, v86, v4, vcc
	v_add_u32_e32 v4, 0xffffff80, v43
	v_cvt_f32_i32_e32 v61, v4
	v_cmp_gt_u32_e32 vcc, s19, v4
	v_max3_f32 v25, v25, v6, v7
	s_cmp_lg_u32 s33, 64
	v_pk_mul_f32 v[4:5], v[62:63], v[60:61]
	v_mov_b32_e32 v62, v1
	v_sub_f32_e32 v0, v4, v5
	v_cndmask_b32_e32 v4, v86, v0, vcc
	v_add_u32_e32 v0, 16, v41
	v_cvt_f32_i32_e32 v61, v0
	v_cmp_gt_u32_e32 vcc, s19, v0
	v_pk_mul_f32 v[0:1], v[62:63], v[60:61]
	s_nop 0
	v_sub_f32_e32 v0, v0, v1
	v_cndmask_b32_e32 v5, v86, v0, vcc
	v_add_u32_e32 v0, 0xffffff7e, v43
	v_cvt_f32_i32_e32 v61, v0
	v_mov_b32_e32 v62, v2
	v_cmp_gt_u32_e32 vcc, s19, v0
	v_max3_f32 v25, v25, v4, v5
	v_pk_mul_f32 v[0:1], v[62:63], v[60:61]
	v_mov_b32_e32 v62, v3
	v_sub_f32_e32 v0, v0, v1
	v_cndmask_b32_e32 v2, v86, v0, vcc
	v_add_u32_e32 v0, 0xffffff7d, v43
	v_cvt_f32_i32_e32 v61, v0
	v_cmp_gt_u32_e32 vcc, s19, v0
	v_pk_mul_f32 v[0:1], v[62:63], v[60:61]
	s_nop 0
	v_sub_f32_e32 v0, v0, v1
	v_cndmask_b32_e32 v3, v86, v0, vcc
	v_add_u32_e32 v0, 0xffffff70, v43
	v_cvt_f32_i32_e32 v61, v0
	v_mov_b32_e32 v62, v32
	v_cmp_gt_u32_e32 vcc, s19, v0
	v_max3_f32 v25, v25, v2, v3
	v_pk_mul_f32 v[0:1], v[62:63], v[60:61]
	v_cvt_f32_i32_e32 v61, v41
	v_sub_f32_e32 v0, v0, v1
	v_mov_b32_e32 v62, v33
	v_cndmask_b32_e32 v59, v86, v0, vcc
	v_pk_mul_f32 v[0:1], v[62:63], v[60:61]
	v_cmp_gt_u32_e32 vcc, s19, v41
	v_sub_f32_e32 v0, v0, v1
	v_mov_b32_e32 v62, v34
	v_cndmask_b32_e32 v41, v86, v0, vcc
	v_add_u32_e32 v0, 0xffffff6e, v43
	v_cvt_f32_i32_e32 v61, v0
	v_cmp_gt_u32_e32 vcc, s19, v0
	v_max3_f32 v25, v25, v59, v41
	v_pk_mul_f32 v[0:1], v[62:63], v[60:61]
	s_nop 0
	v_sub_f32_e32 v0, v0, v1
	v_cndmask_b32_e32 v91, v86, v0, vcc
	v_add_u32_e32 v0, 0xffffff6d, v43
	v_cvt_f32_i32_e32 v61, v0
	v_mov_b32_e32 v62, v35
	v_cmp_gt_u32_e32 vcc, s19, v0
	v_pk_mul_f32 v[0:1], v[62:63], v[60:61]
	s_nop 0
	v_sub_f32_e32 v0, v0, v1
	v_cndmask_b32_e32 v0, v86, v0, vcc
	v_max3_f32 v1, v25, v91, v0
	ds_bpermute_b32 v25, v76, v1
	s_waitcnt lgkmcnt(0)
	v_max_f32_e32 v25, v25, v25
	v_max_f32_e32 v1, v1, v25
	ds_bpermute_b32 v25, v77, v1
	s_waitcnt lgkmcnt(0)
	v_max_f32_e32 v25, v25, v25
	v_max_f32_e32 v1, v1, v25
	v_sub_f32_e32 v27, v42, v1
	v_mul_f32_e32 v27, 0x3fb8aa3b, v27
	v_exp_f32_e32 v42, v27
	v_sub_f32_e32 v27, v38, v1
	v_mul_f32_e32 v27, 0x3fb8aa3b, v27
	v_exp_f32_e32 v38, v27
	v_sub_f32_e32 v27, v39, v1
	v_sub_f32_e32 v25, v40, v1
	v_mul_f32_e32 v27, 0x3fb8aa3b, v27
	v_mul_f32_e32 v25, 0x3fb8aa3b, v25
	v_exp_f32_e32 v39, v27
	v_sub_f32_e32 v27, v36, v1
	v_exp_f32_e32 v40, v25
	v_mul_f32_e32 v27, 0x3fb8aa3b, v27
	v_exp_f32_e32 v43, v27
	v_sub_f32_e32 v27, v37, v1
	v_mul_f32_e32 v27, 0x3fb8aa3b, v27
	v_exp_f32_e32 v61, v27
	v_sub_f32_e32 v27, v30, v1
	v_add_f32_e32 v25, 0, v40
	v_mul_f32_e32 v27, 0x3fb8aa3b, v27
	v_add_f32_e32 v25, v42, v25
	v_exp_f32_e32 v62, v27
	v_sub_f32_e32 v27, v31, v1
	v_add_f32_e32 v25, v38, v25
	v_mul_f32_e32 v27, 0x3fb8aa3b, v27
	v_add_f32_e32 v25, v39, v25
	v_exp_f32_e32 v92, v27
	v_add_f32_e32 v25, v43, v25
	v_add_f32_e32 v25, v61, v25
	v_add_f32_e32 v25, v62, v25
	v_add_f32_e32 v27, v92, v25
	v_sub_f32_e32 v25, v28, v1
	v_mul_f32_e32 v25, 0x3fb8aa3b, v25
	v_exp_f32_e32 v25, v25
	v_sub_f32_e32 v26, v26, v1
	v_mul_f32_e32 v26, 0x3fb8aa3b, v26
	v_sub_f32_e32 v24, v24, v1
	v_add_f32_e32 v28, v25, v27
	v_sub_f32_e32 v27, v29, v1
	v_mul_f32_e32 v27, 0x3fb8aa3b, v27
	v_exp_f32_e32 v27, v27
	v_exp_f32_e32 v29, v26
	v_mul_f32_e32 v24, 0x3fb8aa3b, v24
	v_exp_f32_e32 v33, v24
	v_add_f32_e32 v28, v27, v28
	v_add_f32_e32 v26, v29, v28
	v_sub_f32_e32 v28, v90, v1
	v_mul_f32_e32 v28, 0x3fb8aa3b, v28
	v_exp_f32_e32 v31, v28
	v_sub_f32_e32 v22, v22, v1
	v_mul_f32_e32 v22, 0x3fb8aa3b, v22
	v_sub_f32_e32 v23, v23, v1
	v_add_f32_e32 v26, v31, v26
	v_add_f32_e32 v24, v33, v26
	v_sub_f32_e32 v26, v87, v1
	v_mul_f32_e32 v26, 0x3fb8aa3b, v26
	v_exp_f32_e32 v35, v26
	v_exp_f32_e32 v36, v22
	v_mul_f32_e32 v23, 0x3fb8aa3b, v23
	v_exp_f32_e32 v37, v23
	v_add_f32_e32 v24, v35, v24
	v_sub_f32_e32 v20, v20, v1
	v_add_f32_e32 v22, v36, v24
	v_mul_f32_e32 v20, 0x3fb8aa3b, v20
	v_add_f32_e32 v23, v37, v22
	v_exp_f32_e32 v22, v20
	v_sub_f32_e32 v21, v21, v1
	v_mul_f32_e32 v21, 0x3fb8aa3b, v21
	v_sub_f32_e32 v18, v18, v1
	v_add_f32_e32 v20, v22, v23
	v_exp_f32_e32 v23, v21
	v_mul_f32_e32 v18, 0x3fb8aa3b, v18
	v_sub_f32_e32 v19, v19, v1
	v_exp_f32_e32 v24, v18
	v_mul_f32_e32 v19, 0x3fb8aa3b, v19
	v_sub_f32_e32 v16, v16, v1
	v_exp_f32_e32 v26, v19
	v_mul_f32_e32 v16, 0x3fb8aa3b, v16
	v_sub_f32_e32 v17, v17, v1
	v_exp_f32_e32 v28, v16
	v_mul_f32_e32 v17, 0x3fb8aa3b, v17
	v_sub_f32_e32 v14, v14, v1
	v_add_f32_e32 v20, v23, v20
	v_exp_f32_e32 v30, v17
	v_mul_f32_e32 v14, 0x3fb8aa3b, v14
	v_sub_f32_e32 v15, v15, v1
	v_add_f32_e32 v18, v24, v20
	v_exp_f32_e32 v32, v14
	v_mul_f32_e32 v15, 0x3fb8aa3b, v15
	v_add_f32_e32 v18, v26, v18
	v_exp_f32_e32 v34, v15
	v_add_f32_e32 v16, v28, v18
	v_add_f32_e32 v16, v30, v16
	v_sub_f32_e32 v12, v12, v1
	v_add_f32_e32 v14, v32, v16
	v_mul_f32_e32 v12, 0x3fb8aa3b, v12
	v_add_f32_e32 v15, v34, v14
	v_exp_f32_e32 v14, v12
	v_sub_f32_e32 v13, v13, v1
	v_mul_f32_e32 v13, 0x3fb8aa3b, v13
	v_sub_f32_e32 v10, v10, v1
	v_add_f32_e32 v12, v14, v15
	v_exp_f32_e32 v15, v13
	v_mul_f32_e32 v10, 0x3fb8aa3b, v10
	v_sub_f32_e32 v11, v11, v1
	v_exp_f32_e32 v16, v10
	v_mul_f32_e32 v11, 0x3fb8aa3b, v11
	v_sub_f32_e32 v8, v8, v1
	v_exp_f32_e32 v17, v11
	v_mul_f32_e32 v8, 0x3fb8aa3b, v8
	v_sub_f32_e32 v9, v9, v1
	v_exp_f32_e32 v18, v8
	v_mul_f32_e32 v9, 0x3fb8aa3b, v9
	v_sub_f32_e32 v6, v6, v1
	v_add_f32_e32 v12, v15, v12
	v_exp_f32_e32 v19, v9
	v_mul_f32_e32 v6, 0x3fb8aa3b, v6
	v_sub_f32_e32 v7, v7, v1
	v_add_f32_e32 v10, v16, v12
	v_exp_f32_e32 v20, v6
	v_mul_f32_e32 v7, 0x3fb8aa3b, v7
	v_add_f32_e32 v10, v17, v10
	v_exp_f32_e32 v21, v7
	v_add_f32_e32 v8, v18, v10
	v_add_f32_e32 v8, v19, v8
	v_sub_f32_e32 v4, v4, v1
	v_add_f32_e32 v6, v20, v8
	v_mul_f32_e32 v4, 0x3fb8aa3b, v4
	v_add_f32_e32 v7, v21, v6
	v_exp_f32_e32 v6, v4
	v_sub_f32_e32 v3, v3, v1
	v_sub_f32_e32 v5, v5, v1
	v_mul_f32_e32 v3, 0x3fb8aa3b, v3
	v_mul_f32_e32 v5, 0x3fb8aa3b, v5
	v_sub_f32_e32 v2, v2, v1
	v_exp_f32_e32 v9, v3
	v_sub_f32_e32 v3, v59, v1
	v_add_f32_e32 v4, v6, v7
	v_exp_f32_e32 v7, v5
	v_mul_f32_e32 v2, 0x3fb8aa3b, v2
	v_mul_f32_e32 v3, 0x3fb8aa3b, v3
	v_exp_f32_e32 v8, v2
	v_exp_f32_e32 v10, v3
	v_sub_f32_e32 v3, v41, v1
	v_mul_f32_e32 v3, 0x3fb8aa3b, v3
	v_exp_f32_e32 v11, v3
	v_sub_f32_e32 v3, v91, v1
	v_add_f32_e32 v4, v7, v4
	v_mul_f32_e32 v3, 0x3fb8aa3b, v3
	v_sub_f32_e32 v0, v0, v1
	v_add_f32_e32 v2, v8, v4
	v_exp_f32_e32 v12, v3
	v_mul_f32_e32 v0, 0x3fb8aa3b, v0
	v_add_f32_e32 v2, v9, v2
	v_exp_f32_e32 v13, v0
	v_add_f32_e32 v2, v10, v2
	v_add_f32_e32 v2, v11, v2
	v_add_f32_e32 v2, v12, v2
	v_add_f32_e32 v0, v13, v2
	ds_bpermute_b32 v2, v76, v0
	v_sub_f32_e32 v1, v53, v1
	v_mul_f32_e32 v1, 0x3fb8aa3b, v1
	v_exp_f32_e32 v4, v1
	v_cvt_pk_bf16_f32 v1, v38, v39
	s_waitcnt lgkmcnt(0)
	v_add_f32_e32 v0, v0, v2
	ds_bpermute_b32 v2, v77, v0
	v_add_u32_e32 v39, 0x2000, v57
	v_add_u32_e32 v59, 0x4800, v57
	v_cvt_pk_bf16_f32 v3, v62, v92
	ds_read2_b64 v[90:93], v39 offset0:160 offset1:164
	s_waitcnt lgkmcnt(1)
	v_add_f32_e32 v5, v0, v2
	v_cvt_pk_bf16_f32 v0, v40, v42
	v_cvt_pk_bf16_f32 v2, v43, v61
	ds_read2_b64 v[40:43], v57 offset1:4
	v_add_u32_e32 v61, 0x6800, v57
	ds_read2_b64 v[98:101], v59 offset0:64 offset1:68
	ds_read2_b64 v[102:105], v61 offset0:224 offset1:228
	s_waitcnt lgkmcnt(2)
	v_mfma_f32_16x16x32_bf16 v[40:43], v[40:43], v[0:3], 0
	v_cvt_pk_bf16_f32 v22, v22, v23
	v_cvt_pk_bf16_f32 v23, v24, v26
	v_cvt_pk_bf16_f32 v24, v28, v30
	v_mfma_f32_16x16x32_bf16 v[90:93], v[90:93], v[0:3], 0
	v_cvt_pk_bf16_f32 v14, v14, v15
	v_cvt_pk_bf16_f32 v15, v16, v17
	v_cvt_pk_bf16_f32 v16, v18, v19
	s_waitcnt lgkmcnt(1)
	v_mfma_f32_16x16x32_bf16 v[98:101], v[98:101], v[0:3], 0
	v_cvt_pk_bf16_f32 v17, v20, v21
	ds_read2_b64 v[18:21], v57 offset0:24 offset1:28
	v_cvt_pk_bf16_f32 v6, v6, v7
	s_waitcnt lgkmcnt(1)
	v_mfma_f32_16x16x32_bf16 v[0:3], v[102:105], v[0:3], 0
	v_cvt_pk_bf16_f32 v102, v25, v27
	v_cvt_pk_bf16_f32 v103, v29, v31
	v_cvt_pk_bf16_f32 v104, v33, v35
	v_cvt_pk_bf16_f32 v105, v36, v37
	ds_read2_b64 v[26:29], v57 offset0:16 offset1:20
	v_cvt_pk_bf16_f32 v25, v32, v34
	v_mfma_f32_16x16x32_bf16 v[40:43], v[106:109], v[102:105], v[40:43]
	ds_read2_b64 v[106:109], v39 offset0:168 offset1:172
	ds_read2_b64 v[30:33], v39 offset0:176 offset1:180
	ds_read2_b64 v[34:37], v59 offset0:80 offset1:84
	s_waitcnt lgkmcnt(2)
	v_mfma_f32_16x16x32_bf16 v[90:93], v[106:109], v[102:105], v[90:93]
	ds_read2_b64 v[106:109], v59 offset0:72 offset1:76
	v_cvt_pk_bf16_f32 v7, v8, v9
	v_cvt_pk_bf16_f32 v8, v10, v11
	s_waitcnt lgkmcnt(0)
	v_mfma_f32_16x16x32_bf16 v[98:101], v[106:109], v[102:105], v[98:101]
	ds_read2_b64 v[106:109], v61 offset0:232 offset1:236
	v_cvt_pk_bf16_f32 v9, v12, v13
	ds_read2_b64 v[10:13], v57 offset0:32 offset1:36
	v_mfma_f32_16x16x32_bf16 v[26:29], v[26:29], v[22:25], v[40:43]
	v_add_f32_e32 v4, v4, v5
	v_div_scale_f32 v5, s[6:7], v4, v4, 1.0
	s_nop 0
	ds_read2_b64 v[40:43], v61 offset0:240 offset1:244
	s_waitcnt lgkmcnt(2)
	v_mfma_f32_16x16x32_bf16 v[0:3], v[106:109], v[102:105], v[0:3]
	v_add_u32_e32 v38, 32, v57
	v_mfma_f32_16x16x32_bf16 v[30:33], v[30:33], v[22:25], v[90:93]
	v_mfma_f32_16x16x32_bf16 v[34:37], v[34:37], v[22:25], v[98:101]
	s_waitcnt lgkmcnt(0)
	v_mfma_f32_16x16x32_bf16 v[0:3], v[40:43], v[22:25], v[0:3]
	ds_read2_b64 v[22:25], v39 offset0:184 offset1:188
	v_mfma_f32_16x16x32_bf16 v[18:21], v[18:21], v[14:17], v[26:29]
	s_waitcnt lgkmcnt(0)
	v_mfma_f32_16x16x32_bf16 v[22:25], v[22:25], v[14:17], v[30:33]
	s_nop 0
	ds_read2_b64 v[26:29], v59 offset0:88 offset1:92
	s_nop 0
	ds_read2_b64 v[30:33], v61 offset0:248 offset1:252
	s_waitcnt lgkmcnt(1)
	v_mfma_f32_16x16x32_bf16 v[26:29], v[26:29], v[14:17], v[34:37]
	s_waitcnt lgkmcnt(0)
	v_mfma_f32_16x16x32_bf16 v[0:3], v[30:33], v[14:17], v[0:3]
	ds_read2_b64 v[14:17], v39 offset0:192 offset1:196
	s_waitcnt lgkmcnt(0)
	v_mfma_f32_16x16x32_bf16 v[14:17], v[14:17], v[6:9], v[22:25]
	s_nop 2
	v_add_u32_e32 v22, 0x7000, v57
	ds_read2_b64 v[22:25], v22 offset1:4
	v_mov_b32_e32 v57, v38
	v_mfma_f32_16x16x32_bf16 v[10:13], v[10:13], v[6:9], v[18:21]
	s_nop 2
	ds_read2_b64 v[18:21], v59 offset0:96 offset1:100
	s_waitcnt lgkmcnt(0)
	v_mfma_f32_16x16x32_bf16 v[18:21], v[18:21], v[6:9], v[26:29]
	v_mfma_f32_16x16x32_bf16 v[0:3], v[22:25], v[6:9], v[0:3]
	v_rcp_f32_e32 v6, v5
	s_nop 0
	v_fma_f32 v7, -v5, v6, 1.0
	v_fmac_f32_e32 v6, v7, v6
	v_div_scale_f32 v7, vcc, 1.0, v4, 1.0
	v_mul_f32_e32 v8, v7, v6
	v_fma_f32 v9, -v5, v8, v7
	v_fmac_f32_e32 v8, v9, v6
	v_fma_f32 v5, -v5, v8, v7
	v_div_fmas_f32 v5, v5, v6, v8
	v_div_fixup_f32 v4, v5, v4, 1.0
	v_lshlrev_b64 v[6:7], 11, v[72:73]
	v_pk_mul_f32 v[8:9], v[10:11], v[4:5] op_sel_hi:[1,0]
	v_pk_mul_f32 v[10:11], v[12:13], v[4:5] op_sel_hi:[1,0]
	v_lshl_add_u64 v[6:7], v[68:69], 0, v[6:7]
	v_cvt_pk_bf16_f32 v8, v8, v9
	v_cvt_pk_bf16_f32 v9, v10, v11
	global_store_dwordx2 v[6:7], v[8:9], off
	v_pk_mul_f32 v[8:9], v[4:5], v[14:15] op_sel_hi:[0,1]
	v_pk_mul_f32 v[10:11], v[4:5], v[16:17] op_sel_hi:[0,1]
	v_cvt_pk_bf16_f32 v8, v8, v9
	v_cvt_pk_bf16_f32 v9, v10, v11
	global_store_dwordx2 v[6:7], v[8:9], off offset:32
	v_pk_mul_f32 v[8:9], v[4:5], v[18:19] op_sel_hi:[0,1]
	v_pk_mul_f32 v[10:11], v[4:5], v[20:21] op_sel_hi:[0,1]
	v_pk_mul_f32 v[0:1], v[4:5], v[0:1] op_sel_hi:[0,1]
	v_pk_mul_f32 v[2:3], v[4:5], v[2:3] op_sel_hi:[0,1]
	v_cvt_pk_bf16_f32 v8, v8, v9
	v_cvt_pk_bf16_f32 v9, v10, v11
	v_cvt_pk_bf16_f32 v0, v0, v1
	v_cvt_pk_bf16_f32 v1, v2, v3
	global_store_dwordx2 v[6:7], v[8:9], off offset:64
	global_store_dwordx2 v[6:7], v[0:1], off offset:96
	s_cbranch_scc1 .LBB0_985
	s_add_i32 s29, s29, s94
	s_add_i32 s14, s14, s15
	s_cmpk_gt_i32 s29, 0xff
	s_barrier
	s_cbranch_scc0 .LBB0_976
